# static wave priority: in the scan phase the four recurrence (consumer) waves run at s_setprio 1, producers at 0; all other phases at 0
# speedup vs baseline: 1.0066x; 1.0003x over previous
.LBB0_237:
	v_writelane_b32 v192, s58, 53
	s_nop 1
	v_writelane_b32 v192, s59, 54
	s_or_b64 exec, exec, s[0:1]
	s_add_u32 s76, s84, 0x52a0880
	s_addc_u32 s77, s85, 0
	s_cmpk_gt_i32 s2, 0x5f
	v_writelane_b32 v192, s56, 55
	s_waitcnt lgkmcnt(0)
	s_barrier
	s_cselect_b32 s99, 1, 0
	s_setprio 0
	s_cmp_lg_u32 s99, 0
	v_writelane_b32 v192, s57, 56
	s_cbranch_scc1 .LBB0_308
	s_add_u32 s10, s84, 0x73988c0
	s_addc_u32 s11, s85, 0
	s_movk_i32 s3, 0x90
	s_movk_i32 s15, 0x84
	s_movk_i32 s38, 0x6000
	v_mov_b32_e32 v0, 0
	s_movk_i32 s39, 0x880
	s_mov_b64 s[12:13], 0x100
	s_mov_b32 s40, s2
	s_branch .LBB0_240

.LBB0_360:
	s_or_b64 exec, exec, s[0:1]
	s_add_u32 s88, s84, 0x3018000
	s_addc_u32 s89, s85, 0
	s_add_u32 s28, s84, 0xbad88c0
	s_addc_u32 s29, s85, 0
	s_lshl_b32 s0, s86, 3
	s_waitcnt lgkmcnt(0)
	v_mov_b32_e32 v0, v174
	v_writelane_b32 v192, s0, 57
	s_barrier
	s_cselect_b32 s99, 1, 0
	s_setprio 0
	s_cmp_lg_u32 s99, 0
	s_nop 0
	v_writelane_b32 v192, s1, 58
	s_waitcnt vmcnt(3)
	v_ashrrev_i32_e32 v64, 6, v0
	s_lshl_b32 s0, s2, 3
	v_writelane_b32 v192, s0, 59
	v_add_u32_e32 v137, s0, v64
	s_movk_i32 s0, 0x810
	v_cmp_gt_i32_e32 vcc, s0, v137
	v_mbcnt_lo_u32_b32 v175, -1, 0
	s_and_saveexec_b64 s[4:5], vcc
	s_cbranch_execz .LBB0_379
	v_readlane_b32 s52, v192, 11
	v_readlane_b32 s53, v192, 12
	v_readlane_b32 s54, v192, 13
	v_readlane_b32 s55, v192, 14
	v_readlane_b32 s64, v192, 23
	v_readlane_b32 s65, v192, 24
	s_mov_b64 s[40:41], s[52:53]
	v_readlane_b32 s66, v192, 25
	v_readlane_b32 s67, v192, 26
	s_mov_b64 s[42:43], s[54:55]
	s_mov_b64 s[52:53], s[64:65]
	s_mov_b64 s[54:55], s[66:67]
	v_lshlrev_b32_e32 v0, 2, v0
	s_add_u32 s0, s54, 0x2000
	v_and_b32_e32 v136, 0xfc, v0
	s_addc_u32 s1, s55, 0
	s_add_u32 s6, s54, 0x3000
	v_lshlrev_b32_e32 v138, 2, v136
	s_addc_u32 s7, s55, 0
	global_load_dwordx4 v[0:3], v138, s[40:41]
	global_load_dwordx4 v[4:7], v138, s[54:55]
	global_load_dwordx4 v[8:11], v138, s[0:1]
	global_load_dwordx4 v[12:15], v138, s[6:7]
	v_or_b32_e32 v66, 0x100, v136
	s_waitcnt vmcnt(4)
	v_or_b32_e32 v68, 0x200, v136
	v_or_b32_e32 v70, 0x300, v136
	v_lshlrev_b32_e32 v28, 2, v66
	v_lshlrev_b32_e32 v44, 2, v68
	v_lshlrev_b32_e32 v60, 2, v70
	global_load_dwordx4 v[16:19], v138, s[40:41] offset:1024
	global_load_dwordx4 v[20:23], v138, s[54:55] offset:1024
	global_load_dwordx4 v[24:27], v28, s[0:1]
	s_nop 0
	global_load_dwordx4 v[28:31], v28, s[6:7]
	s_nop 0
	global_load_dwordx4 v[32:35], v138, s[40:41] offset:2048
	global_load_dwordx4 v[36:39], v138, s[54:55] offset:2048
	global_load_dwordx4 v[40:43], v44, s[0:1]
	s_nop 0
	global_load_dwordx4 v[44:47], v44, s[6:7]
	s_nop 0
	global_load_dwordx4 v[48:51], v138, s[40:41] offset:3072
	global_load_dwordx4 v[52:55], v138, s[54:55] offset:3072
	global_load_dwordx4 v[56:59], v60, s[0:1]
	s_nop 0
	global_load_dwordx4 v[60:63], v60, s[6:7]
	v_mbcnt_hi_u32_b32 v65, -1, v175
	v_and_b32_e32 v67, 64, v65
	v_add_u32_e32 v67, 64, v67
	v_xor_b32_e32 v69, 32, v65
	v_cmp_lt_i32_e32 vcc, v69, v67
	v_readlane_b32 s36, v192, 37
	v_mov_b32_e32 v139, 0
	v_cndmask_b32_e32 v69, v65, v69, vcc
	v_lshlrev_b32_e32 v176, 2, v69
	v_xor_b32_e32 v69, 16, v65
	v_cmp_lt_i32_e32 vcc, v69, v67
	v_readlane_b32 s37, v192, 38
	v_readlane_b32 s46, v192, 47
	v_cndmask_b32_e32 v69, v65, v69, vcc
	v_lshlrev_b32_e32 v177, 2, v69
	v_xor_b32_e32 v69, 8, v65
	v_cmp_lt_i32_e32 vcc, v69, v67
	v_readlane_b32 s47, v192, 48
	s_add_u32 s6, s82, 0x6180000
	v_cndmask_b32_e32 v69, v65, v69, vcc
	v_lshlrev_b32_e32 v178, 2, v69
	v_xor_b32_e32 v69, 4, v65
	v_cmp_lt_i32_e32 vcc, v69, v67
	v_lshl_add_u64 v[140:141], s[36:37], 0, v[138:139]
	v_lshl_add_u64 v[142:143], s[46:47], 0, v[138:139]
	v_cndmask_b32_e32 v69, v65, v69, vcc
	v_lshlrev_b32_e32 v179, 2, v69
	v_xor_b32_e32 v69, 2, v65
	v_cmp_lt_i32_e32 vcc, v69, v67
	s_addc_u32 s7, s83, 0
	v_lshlrev_b32_e32 v138, 1, v136
	v_cndmask_b32_e32 v69, v65, v69, vcc
	v_lshlrev_b32_e32 v180, 2, v69
	v_xor_b32_e32 v69, 1, v65
	v_cmp_lt_i32_e32 vcc, v69, v67
	v_readlane_b32 s94, v192, 27
	v_readlane_b32 s38, v192, 39
	v_cndmask_b32_e32 v65, v65, v69, vcc
	v_readlane_b32 s39, v192, 40
	v_readlane_b32 s40, v192, 41
	s_add_u32 s8, s82, 0x6184000
	v_lshl_add_u64 v[146:147], s[82:83], 0, v[138:139]
	s_mov_b64 s[0:1], 0x2040000
	v_lshlrev_b32_e32 v64, 3, v64
	v_readlane_b32 s95, v192, 28
	v_lshlrev_b32_e32 v181, 2, v65
	s_addc_u32 s9, s83, 0
	v_lshl_add_u64 v[144:145], s[88:89], 0, v[138:139]
	v_lshl_add_u64 v[148:149], v[146:147], 0, s[0:1]
	v_lshl_add_u64 v[150:151], s[28:29], 0, v[138:139]
	v_lshl_add_u32 v182, s2, 6, v64
	s_lshl_b32 s3, s86, 6
	s_mov_b64 s[10:11], 0
	s_movk_i32 s15, 0x800
	v_mov_b32_e32 v183, 0x358637bd
	s_mov_b32 s18, 0x800000
	s_movk_i32 s19, 0x6000
	s_mov_b64 s[12:13], 0x1000
	s_movk_i32 s34, 0x3fff
	s_movk_i32 s35, 0x4000
	v_lshlrev_b32_e32 v152, 2, v66
	v_lshlrev_b32_e32 v154, 2, v68
	v_lshlrev_b32_e32 v156, 2, v70
	s_movk_i32 s38, 0xfff
	s_movk_i32 s39, 0x880
	s_movk_i32 s40, 0x80f
	v_readlane_b32 s56, v192, 15
	v_readlane_b32 s57, v192, 16
	v_readlane_b32 s58, v192, 17
	v_readlane_b32 s59, v192, 18
	v_readlane_b32 s60, v192, 19
	v_readlane_b32 s61, v192, 20
	v_readlane_b32 s62, v192, 21
	v_readlane_b32 s63, v192, 22
	v_readlane_b32 s41, v192, 42
	v_readlane_b32 s42, v192, 43
	v_readlane_b32 s43, v192, 44
	v_readlane_b32 s44, v192, 45
	v_readlane_b32 s45, v192, 46
	v_readlane_b32 s48, v192, 49
	v_readlane_b32 s49, v192, 50
	v_readlane_b32 s50, v192, 51
	v_readlane_b32 s51, v192, 52
	s_branch .LBB0_363

.LBB0_431:
	s_or_b64 exec, exec, s[0:1]
	s_cmpk_gt_i32 s2, 0x3ce
	s_waitcnt lgkmcnt(0)
	s_barrier
	s_cselect_b32 s99, 1, 0
	s_setprio 0
	s_cmp_lg_u32 s99, 0
	s_cbranch_scc1 .LBB0_849
	s_add_u32 s36, s84, 0xfb588c0
	s_addc_u32 s37, s85, 0
	s_add_u32 s3, s84, 0x880000
	s_addc_u32 s15, s85, 0
	s_add_u32 s16, s84, 0x880100
	v_readlane_b32 s52, v192, 11
	s_addc_u32 s17, s85, 0
	s_add_i32 s40, s2, 0xfffffcf4
	s_add_i32 s41, s2, 0xfff4
	v_readlane_b32 s66, v192, 25
	v_readlane_b32 s53, v192, 12
	v_readlane_b32 s54, v192, 13
	v_readlane_b32 s55, v192, 14
	v_readlane_b32 s67, v192, 26
	s_add_u32 s46, s66, 0x218
	s_addc_u32 s48, s67, 0
	s_movk_i32 s49, 0x90
	s_mov_b32 s39, 0
	s_movk_i32 s45, 0x4080
	v_mov_b32_e32 v0, 0
	s_movk_i32 s47, 0x440
	s_movk_i32 s52, 0x880
	s_mov_b64 s[42:43], 0x80
	s_add_i32 s53, 0, 0x10000
	s_add_i32 s54, 0, 0x14000
	v_mov_b32_e32 v168, 0x4100
	v_mov_b32_e32 v169, 0x22000
	v_mov_b32_e32 v170, 0x88000
	s_mov_b32 s55, s2
	v_readlane_b32 s56, v192, 15
	v_readlane_b32 s57, v192, 16
	v_readlane_b32 s58, v192, 17
	v_readlane_b32 s59, v192, 18
	v_readlane_b32 s60, v192, 19
	v_readlane_b32 s61, v192, 20
	v_readlane_b32 s62, v192, 21
	v_readlane_b32 s63, v192, 22
	v_readlane_b32 s64, v192, 23
	v_readlane_b32 s65, v192, 24
	s_branch .LBB0_435

.LBB0_901:
	s_or_b64 exec, exec, s[0:1]
	s_mov_b32 s0, 0x8000
	v_cmp_gt_i32_e32 vcc, s0, v158
	s_waitcnt lgkmcnt(0)
	s_barrier
	s_cselect_b32 s99, 1, 0
	s_setprio 0
	s_cmp_lg_u32 s99, 0
	s_and_saveexec_b64 s[0:1], vcc
	v_readlane_b32 s52, v192, 37
	v_readlane_b32 s54, v192, 39
	v_readlane_b32 s55, v192, 40
	v_readlane_b32 s53, v192, 38
	v_readlane_b32 s56, v192, 41
	v_readlane_b32 s57, v192, 42
	v_readlane_b32 s58, v192, 43
	v_readlane_b32 s59, v192, 44
	v_readlane_b32 s60, v192, 45
	v_readlane_b32 s61, v192, 46
	v_readlane_b32 s62, v192, 47
	v_readlane_b32 s63, v192, 48
	v_readlane_b32 s64, v192, 49
	v_readlane_b32 s65, v192, 50
	v_readlane_b32 s66, v192, 51
	v_readlane_b32 s67, v192, 52
	s_cbranch_execz .LBB0_904
	s_add_u32 s4, s82, 0x4000000
	s_addc_u32 s5, s83, 0
	s_ashr_i32 s15, s14, 31
	v_lshlrev_b64 v[0:1], 4, v[158:159]
	s_lshl_b64 s[6:7], s[14:15], 4
	s_mov_b64 s[8:9], 0
	s_movk_i32 s3, 0x7fff

.LBB0_1107:
	s_or_b64 exec, exec, s[0:1]
	s_add_u32 s62, s84, 0x7a588c0
	s_addc_u32 s63, s85, 0
	s_add_u32 s54, s84, 0x9a988c0
	s_addc_u32 s55, s85, 0
	s_add_u32 s66, s84, 0xdb188c0
	s_addc_u32 s67, s85, 0
	s_add_u32 s58, s84, 0x59108c0
	v_mov_b32_e32 v19, v174
	s_addc_u32 s59, s85, 0
	s_waitcnt lgkmcnt(0)
	s_barrier
	s_cselect_b32 s99, 1, 0
	s_setprio 0
	v_readfirstlane_b32 s98, v174
	s_lshr_b32 s98, s98, 6
	s_cmp_ge_u32 s98, 4
	s_cbranch_scc1 .Lpr5_skip
	s_setprio 1
.Lpr5_skip:
	s_cmp_lg_u32 s99, 0
	s_cmpk_gt_i32 s2, 0xff
	v_lshl_add_u32 v21, v19, 2, 0
	s_cbranch_scc1 .LBB0_1184
	v_add_u32_e32 v1, 0xffffff00, v19
	v_bfe_u32 v26, v19, 4, 3
	s_movk_i32 s3, 0x7f
	v_and_b32_e32 v18, 15, v19
	v_cmp_lt_u32_e64 s[14:15], s3, v1
	v_mul_u32_u24_e32 v2, 0x270, v26
	v_and_b32_e32 v1, 0xffffff80, v1
	s_movk_i32 s3, 0x80
	v_lshl_add_u32 v27, v2, 2, 0
	v_lshlrev_b32_e32 v2, 4, v18
	v_cmp_ne_u32_e64 s[6:7], s3, v1
	v_and_b32_e32 v1, 0x7f, v19
	v_lshlrev_b32_e32 v28, 1, v26
	v_add_u32_e32 v29, v27, v2
	v_and_b32_e32 v2, 48, v2
	v_lshl_add_u32 v146, v1, 6, 0
	v_or_b32_e32 v1, 0x80, v1
	v_ashrrev_i32_e32 v16, 4, v19
	v_mov_b32_e32 v23, 0
	v_add_u32_e32 v33, v27, v2
	v_lshl_add_u32 v147, v1, 6, 0
	v_lshrrev_b32_e32 v30, 4, v1
	v_mul_u32_u24_e32 v1, 0x880, v26
	v_lshlrev_b32_e32 v2, 1, v18
	v_or_b32_e32 v22, 33, v28
	s_movk_i32 s0, 0x100
	v_ashrrev_i32_e32 v17, 31, v16
	v_lshlrev_b32_e32 v0, 6, v19
	s_mov_b64 s[4:5], 0xff0
	s_add_u32 s34, s82, 0x4080000
	v_or_b32_e32 v34, v1, v2
	v_mov_b64_e32 v[36:37], v[22:23]
	v_mul_u32_u24_e32 v1, 0x880, v30
	v_lshlrev_b32_e32 v22, 7, v26
	s_mov_b64 s[8:9], 0x59114c0
	v_cmp_gt_i32_e64 s[0:1], s0, v19
	v_lshlrev_b32_e32 v20, 2, v18
	v_lshl_add_u64 v[24:25], v[16:17], 0, s[4:5]
	s_mov_b32 s73, 0
	v_cmp_eq_u32_e64 s[4:5], 0, v18
	v_bfe_u32 v31, v19, 2, 2
	s_addc_u32 s35, s83, 0
	v_lshlrev_b32_e32 v32, 12, v26
	s_movk_i32 s40, 0x880
	v_mul_hi_u32_u24_e32 v35, 0x880, v26
	v_mul_hi_u32_u24_e32 v39, 0x880, v30
	v_or_b32_e32 v38, v1, v2
	v_lshl_add_u64 v[40:41], v[22:23], 0, s[8:9]
	v_add_u32_e32 v148, 0, v0
	s_movk_i32 s41, 0x7fff
	s_mov_b32 s3, 1.0
	s_mov_b32 s42, 0xf800000
	v_mov_b32_e32 v149, 0x260
	s_mov_b32 s78, 0x3d800000
	s_mov_b64 s[90:91], 0x22000
	v_mov_b32_e32 v43, 1.0
	v_mov_b32_e32 v150, 0x880
	s_mov_b32 s43, s2
	s_mov_b32 s44, s2
	s_branch .LBB0_1110

.LBB0_1244:
	s_or_b64 exec, exec, s[0:1]
	s_cmpk_gt_i32 s2, 0x103
	s_waitcnt lgkmcnt(0)
	s_barrier
	s_cselect_b32 s99, 1, 0
	s_setprio 0
	s_cmp_lg_u32 s99, 0
	s_cbranch_scc1 .LBB0_1273
	s_add_u32 s4, s84, 0xff688c0
	s_addc_u32 s5, s85, 0
	s_waitcnt vmcnt(22)
	v_mov_b32_e32 v1, 0
	s_mov_b32 s7, 0
	s_mov_b64 s[8:9], 0x80
	s_add_i32 s3, 0, 0x10000
	s_add_i32 s10, 0, 0x14000
	s_mov_b64 s[12:13], 0xc0
	s_add_i32 s11, 0, 0x4000
	s_movk_i32 s14, 0x4080
	s_movk_i32 s15, 0x880
	v_mov_b32_e32 v166, 0x3a27c5ac
	s_mov_b32 s16, 0x800000
	v_mbcnt_hi_u32_b32 v167, -1, v175
	v_mov_b32_e32 v168, 0x407f
	s_mov_b32 s17, s2
	s_branch .LBB0_1247

.LBB0_1325:
	s_or_b64 exec, exec, s[0:1]
	s_cmpk_lt_i32 s2, 0x140
	s_cselect_b64 s[4:5], -1, 0
	s_cmpk_gt_i32 s2, 0x13f
	s_waitcnt lgkmcnt(0)
	s_barrier
	s_cselect_b32 s99, 1, 0
	s_setprio 0
	s_cmp_lg_u32 s99, 0
	s_cbranch_scc1 .LBB0_1468
	s_add_u32 s6, s84, 0x52a2880
	s_addc_u32 s7, s85, 0
	s_movk_i32 s3, 0x4000
	s_movk_i32 s16, 0x880
	s_waitcnt vmcnt(22)
	v_mov_b32_e32 v1, 0
	s_mov_b32 s9, 0
	s_movk_i32 s17, 0x6000
	s_add_i32 s18, 0, 0x10000
	s_add_i32 s19, 0, 0x14000
	s_movk_i32 s20, 0x4080
	s_mov_b32 s21, s2
	s_branch .LBB0_1328

.LBB0_1520:
	s_or_b64 exec, exec, s[0:1]
	v_mov_b32_e32 v32, v174
	s_waitcnt lgkmcnt(0)
	s_barrier
	s_cselect_b32 s99, 1, 0
	s_setprio 0
	s_cmp_lg_u32 s99, 0
	s_movk_i32 s3, 0x4080
	s_waitcnt vmcnt(22)
	v_ashrrev_i32_e32 v0, 6, v32
	v_add_u32_e32 v54, s94, v0
	v_cmp_gt_i32_e32 vcc, s3, v54
	s_mul_hi_i32 s55, s74, 0x880
	s_mul_i32 s54, s74, 0x880
	s_and_saveexec_b64 s[6:7], vcc
	s_cbranch_execz .LBB0_1525
	v_lshlrev_b32_e32 v0, 2, v32
	v_ashrrev_i32_e32 v55, 31, v54
	v_and_b32_e32 v34, 0xfc, v0
	s_waitcnt vmcnt(2)
	v_lshlrev_b64 v[16:17], 12, v[54:55]
	v_mov_b32_e32 v49, 0
	v_lshlrev_b32_e32 v48, 2, v34
	v_readlane_b32 s8, v192, 11
	v_lshl_add_u64 v[16:17], s[82:83], 0, v[16:17]
	v_readlane_b32 s10, v192, 13
	v_readlane_b32 s11, v192, 14
	v_lshl_add_u64 v[16:17], v[16:17], 0, v[48:49]
	s_nop 3
	global_load_dwordx4 v[0:3], v48, s[10:11]
	global_load_dwordx4 v[4:7], v48, s[10:11] offset:1024
	global_load_dwordx4 v[8:11], v48, s[10:11] offset:2048
	global_load_dwordx4 v[12:15], v48, s[10:11] offset:3072
	global_load_dwordx4 v[28:31], v[16:17], off
	global_load_dwordx4 v[24:27], v[16:17], off offset:1024
	global_load_dwordx4 v[20:23], v[16:17], off offset:2048
	s_nop 0
	global_load_dwordx4 v[16:19], v[16:17], off offset:3072
	v_mbcnt_hi_u32_b32 v33, -1, v175
	v_and_b32_e32 v35, 64, v33
	v_add_u32_e32 v35, 64, v35
	v_xor_b32_e32 v36, 32, v33
	v_cmp_lt_i32_e32 vcc, v36, v35
	s_movk_i32 s0, 0x880
	v_readlane_b32 s9, v192, 12
	v_cndmask_b32_e32 v36, v33, v36, vcc
	v_lshlrev_b32_e32 v55, 2, v36
	v_xor_b32_e32 v36, 16, v33
	v_cmp_lt_i32_e32 vcc, v36, v35
	v_readlane_b32 s12, v192, 15
	v_readlane_b32 s13, v192, 16
	v_cndmask_b32_e32 v36, v33, v36, vcc
	v_lshlrev_b32_e32 v56, 2, v36
	v_xor_b32_e32 v36, 8, v33
	v_cmp_lt_i32_e32 vcc, v36, v35
	v_readlane_b32 s14, v192, 17
	v_readlane_b32 s15, v192, 18
	v_cndmask_b32_e32 v36, v33, v36, vcc
	v_lshlrev_b32_e32 v57, 2, v36
	v_xor_b32_e32 v36, 4, v33
	v_cmp_lt_i32_e32 vcc, v36, v35
	v_readlane_b32 s18, v192, 21
	v_readlane_b32 s19, v192, 22
	v_cndmask_b32_e32 v36, v33, v36, vcc
	v_lshlrev_b32_e32 v58, 2, v36
	v_xor_b32_e32 v36, 2, v33
	v_cmp_lt_i32_e32 vcc, v36, v35
	v_readlane_b32 s20, v192, 23
	v_readlane_b32 s21, v192, 24
	v_cndmask_b32_e32 v36, v33, v36, vcc
	v_lshlrev_b32_e32 v59, 2, v36
	v_xor_b32_e32 v36, 1, v33
	v_cmp_lt_i32_e32 vcc, v36, v35
	v_and_b32_e32 v35, 63, v32
	v_lshlrev_b32_e32 v48, 3, v35
	v_cndmask_b32_e32 v33, v33, v36, vcc
	v_lshlrev_b32_e32 v60, 2, v33
	v_mad_i64_i32 v[32:33], s[0:1], v54, s0, v[48:49]
	v_lshl_add_u64 v[32:33], s[84:85], 0, v[32:33]
	s_mov_b64 s[0:1], 0x3018000
	v_lshl_add_u64 v[50:51], v[32:33], 0, s[0:1]
	v_add_u32_e32 v32, s74, v54
	v_ashrrev_i32_e32 v33, 31, v32
	v_lshlrev_b64 v[32:33], 12, v[32:33]
	s_ashr_i32 s75, s74, 31
	v_lshl_or_b32 v32, v35, 4, v32
	v_lshl_add_u64 v[52:53], s[82:83], 0, v[32:33]
	s_lshl_b64 s[8:9], s[74:75], 12
	s_mov_b64 s[10:11], 0
	s_movk_i32 s18, 0x407f
	s_movk_i32 s19, 0x4000
	s_movk_i32 s20, 0x6000
	v_lshlrev_b32_e32 v48, 2, v34
	s_mov_b64 s[12:13], 0x3000
	s_mov_b64 s[14:15], 0x4000
	v_mov_b32_e32 v61, 0x358637bd
	s_mov_b32 s21, 0x800000
	v_readlane_b32 s16, v192, 19
	v_readlane_b32 s17, v192, 20
	v_readlane_b32 s22, v192, 25
	v_readlane_b32 s23, v192, 26
	s_branch .LBB0_1523

.LBB0_1577:
	s_or_b64 exec, exec, s[0:1]
	s_cmpk_lt_i32 s2, 0x410
	s_cselect_b64 s[56:57], -1, 0
	s_cmpk_gt_i32 s2, 0x40f
	s_waitcnt lgkmcnt(0)
	s_barrier
	s_cselect_b32 s99, 1, 0
	s_setprio 0
	s_cmp_lg_u32 s99, 0
	s_cbranch_scc1 .LBB0_1606
	v_readlane_b32 s0, v192, 53
	v_readlane_b32 s1, v192, 54
	s_movk_i32 s3, 0x880
	v_mov_b64_e32 v[158:159], s[88:89]
	v_mov_b64_e32 v[160:161], s[0:1]
	v_mov_b32_e32 v1, 0
	s_mov_b32 s7, 0
	s_mov_b64 s[8:9], 0x80
	s_add_i32 s10, 0, 0x10000
	s_add_i32 s11, 0, 0x14000
	s_movk_i32 s12, 0x4080
	s_movk_i32 s13, 0x2080
	s_mov_b32 s14, s2
	s_waitcnt vmcnt(0)
	s_branch .LBB0_1580

.LBB0_1658:
	s_or_b64 exec, exec, s[0:1]
	s_waitcnt lgkmcnt(0)
	v_cndmask_b32_e64 v0, 0, 1, s[4:5]
	v_cmp_ne_u32_e64 s[72:73], 1, v0
	s_andn2_b64 vcc, exec, s[4:5]
	s_barrier
	s_cselect_b32 s99, 1, 0
	s_setprio 0
	s_cmp_lg_u32 s99, 0
	s_cbranch_vccnz .LBB0_1801
	s_add_u32 s4, s84, 0x52a5880
	s_addc_u32 s5, s85, 0
	s_movk_i32 s3, 0x4000
	s_movk_i32 s16, 0x2080
	v_mov_b32_e32 v1, 0
	s_mov_b32 s7, 0
	s_movk_i32 s17, 0x6000
	s_mov_b64 s[8:9], 0x80
	s_add_i32 s18, 0, 0x10000
	s_add_i32 s19, 0, 0x14000
	s_movk_i32 s20, 0x4080
	s_mov_b32 s21, s2
	s_branch .LBB0_1661

.LBB0_1853:
	s_or_b64 exec, exec, s[0:1]
	v_mov_b32_e32 v32, v174
	s_waitcnt lgkmcnt(0)
	s_barrier
	s_cselect_b32 s99, 1, 0
	s_setprio 0
	s_cmp_lg_u32 s99, 0
	s_movk_i32 s3, 0x4080
	v_ashrrev_i32_e32 v0, 6, v32
	v_add_u32_e32 v54, s94, v0
	v_cmp_gt_i32_e32 vcc, s3, v54
	s_and_saveexec_b64 s[4:5], vcc
	s_cbranch_execz .LBB0_1858
	v_lshlrev_b32_e32 v0, 2, v32
	v_and_b32_e32 v34, 0xfc, v0
	v_readlane_b32 s8, v192, 11
	v_mov_b32_e32 v49, 0
	v_lshlrev_b32_e32 v48, 2, v34
	v_readlane_b32 s9, v192, 12
	v_ashrrev_i32_e32 v55, 31, v54
	s_waitcnt vmcnt(2)
	v_lshlrev_b64 v[16:17], 12, v[54:55]
	v_lshl_add_u64 v[0:1], s[8:9], 0, v[48:49]
	s_mov_b64 s[6:7], 0x1000
	s_waitcnt vmcnt(0)
	v_add_co_u32_e32 v8, vcc, 0x1000, v0
	v_lshl_add_u64 v[16:17], s[82:83], 0, v[16:17]
	v_lshl_add_u64 v[12:13], v[0:1], 0, s[6:7]
	v_addc_co_u32_e32 v9, vcc, 0, v1, vcc
	v_lshl_add_u64 v[16:17], v[16:17], 0, v[48:49]
	global_load_dwordx4 v[0:3], v[12:13], off offset:1024
	global_load_dwordx4 v[4:7], v[12:13], off offset:2048
	s_nop 0
	global_load_dwordx4 v[8:11], v[8:9], off
	s_nop 0
	global_load_dwordx4 v[12:15], v[12:13], off offset:3072
	s_nop 0
	global_load_dwordx4 v[28:31], v[16:17], off
	global_load_dwordx4 v[24:27], v[16:17], off offset:1024
	global_load_dwordx4 v[20:23], v[16:17], off offset:2048
	s_nop 0
	global_load_dwordx4 v[16:19], v[16:17], off offset:3072
	v_mbcnt_hi_u32_b32 v33, -1, v175
	v_and_b32_e32 v35, 64, v33
	v_add_u32_e32 v35, 64, v35
	v_xor_b32_e32 v36, 32, v33
	v_cmp_lt_i32_e32 vcc, v36, v35
	s_movk_i32 s0, 0x880
	v_readlane_b32 s10, v192, 13
	v_cndmask_b32_e32 v36, v33, v36, vcc
	v_lshlrev_b32_e32 v55, 2, v36
	v_xor_b32_e32 v36, 16, v33
	v_cmp_lt_i32_e32 vcc, v36, v35
	v_readlane_b32 s11, v192, 14
	v_readlane_b32 s14, v192, 17
	v_cndmask_b32_e32 v36, v33, v36, vcc
	v_lshlrev_b32_e32 v56, 2, v36
	v_xor_b32_e32 v36, 8, v33
	v_cmp_lt_i32_e32 vcc, v36, v35
	v_readlane_b32 s15, v192, 18
	v_readlane_b32 s16, v192, 19
	v_cndmask_b32_e32 v36, v33, v36, vcc
	v_lshlrev_b32_e32 v57, 2, v36
	v_xor_b32_e32 v36, 4, v33
	v_cmp_lt_i32_e32 vcc, v36, v35
	v_readlane_b32 s17, v192, 20
	v_readlane_b32 s18, v192, 21
	v_cndmask_b32_e32 v36, v33, v36, vcc
	v_lshlrev_b32_e32 v58, 2, v36
	v_xor_b32_e32 v36, 2, v33
	v_cmp_lt_i32_e32 vcc, v36, v35
	s_ashr_i32 s75, s74, 31
	s_movk_i32 s14, 0x1000
	v_cndmask_b32_e32 v36, v33, v36, vcc
	v_lshlrev_b32_e32 v59, 2, v36
	v_xor_b32_e32 v36, 1, v33
	v_cmp_lt_i32_e32 vcc, v36, v35
	v_and_b32_e32 v35, 63, v32
	v_lshlrev_b32_e32 v48, 3, v35
	v_cndmask_b32_e32 v33, v33, v36, vcc
	v_lshlrev_b32_e32 v60, 2, v33
	v_mad_i64_i32 v[32:33], s[0:1], v54, s0, v[48:49]
	v_lshl_add_u64 v[32:33], s[84:85], 0, v[32:33]
	s_mov_b64 s[0:1], 0x3018000
	v_lshl_add_u64 v[50:51], v[32:33], 0, s[0:1]
	v_add_u32_e32 v32, s74, v54
	v_ashrrev_i32_e32 v33, 31, v32
	v_lshlrev_b64 v[32:33], 12, v[32:33]
	v_lshl_or_b32 v32, v35, 4, v32
	v_lshl_add_u64 v[52:53], s[82:83], 0, v[32:33]
	s_lshl_b64 s[8:9], s[74:75], 12
	s_mov_b64 s[10:11], 0
	s_movk_i32 s15, 0x407f
	s_movk_i32 s16, 0x4000
	s_movk_i32 s17, 0x6000
	v_lshlrev_b32_e32 v48, 2, v34
	v_mov_b32_e32 v61, 0x358637bd
	s_mov_b32 s18, 0x800000
	v_readlane_b32 s12, v192, 15
	v_readlane_b32 s13, v192, 16
	v_readlane_b32 s19, v192, 22
	v_readlane_b32 s20, v192, 23
	v_readlane_b32 s21, v192, 24
	v_readlane_b32 s22, v192, 25
	v_readlane_b32 s23, v192, 26
	s_branch .LBB0_1856

.LBB0_1910:
	s_or_b64 exec, exec, s[0:1]
	s_add_u32 s40, s84, 0x9d208c0
	s_addc_u32 s41, s85, 0
	s_add_u32 s58, s84, 0xa5408c0
	s_addc_u32 s59, s85, 0
	s_cmpk_gt_i32 s2, 0x185
	s_waitcnt lgkmcnt(0)
	s_barrier
	s_cselect_b32 s99, 1, 0
	s_setprio 0
	s_cmp_lg_u32 s99, 0
	s_cbranch_scc1 .LBB0_2598
	s_add_u32 s16, s84, 0x58d0880
	s_addc_u32 s17, s85, 0
	s_add_u32 s20, s82, 0x7304000
	s_addc_u32 s21, s83, 0
	s_add_u32 s22, s82, 0x7284000
	s_addc_u32 s23, s83, 0
	s_add_u32 s24, s82, 0x6284000
	s_addc_u32 s25, s83, 0
	v_readlane_b32 s0, v192, 33
	s_add_u32 s26, s82, 0x6204000
	v_readlane_b32 s1, v192, 34
	s_addc_u32 s27, s83, 0
	s_movk_i32 s3, 0x880
	v_mov_b64_e32 v[158:159], s[88:89]
	v_mov_b64_e32 v[160:161], s[0:1]
	v_mov_b32_e32 v1, 0
	s_mov_b32 s19, 0
	s_movk_i32 s42, 0x2000
	s_movk_i32 s43, 0x4000
	s_mov_b64 s[28:29], 0x80
	s_add_i32 s44, 0, 0x10000
	s_add_i32 s45, 0, 0x14000
	s_movk_i32 s47, 0x3fff
	s_movk_i32 s52, 0x4080
	s_movk_i32 s53, 0xf7f
	s_movk_i32 s60, 0x7fff
	v_mov_b32_e32 v170, 0x10000
	v_mov_b32_e32 v171, 0x7f
	s_mov_b32 s61, s2
	s_branch .LBB0_1913

.LBB0_2650:
	s_or_b64 exec, exec, s[0:1]
	s_add_u32 s60, s84, 0x7a988c0
	s_addc_u32 s61, s85, 0
	v_mov_b32_e32 v38, v174
	s_cmpk_gt_i32 s2, 0x1ff
	s_waitcnt lgkmcnt(0)
	s_barrier
	s_cselect_b32 s99, 1, 0
	s_setprio 0
	s_cmp_lg_u32 s99, 0
	s_cbranch_scc1 .LBB0_2698
	v_and_b32_e32 v4, 31, v38
	s_mov_b32 s3, 0x55555556
	v_lshlrev_b32_e32 v43, 3, v4
	s_waitcnt vmcnt(0)
	v_lshl_add_u32 v8, v4, 4, 0
	v_mul_hi_i32 v4, v38, s3
	v_lshrrev_b32_e32 v5, 31, v4
	v_ashrrev_i32_e32 v41, 6, v38
	s_movk_i32 s0, 0x1500
	v_add_u32_e32 v4, v4, v5
	s_movk_i32 s3, 0x230
	v_mul_lo_u32 v0, v41, s0
	s_add_i32 s0, 0, 0x11c00
	v_lshl_add_u32 v5, v4, 1, v4
	v_mul_lo_u32 v4, v4, s3
	v_add_u32_e32 v3, s0, v0
	v_sub_u32_e32 v5, v38, v5
	v_add_u32_e32 v9, 0, v4
	v_bfe_u32 v4, v38, 2, 4
	s_movk_i32 s4, 0x150
	v_lshlrev_b32_e32 v10, 4, v5
	v_lshlrev_b32_e32 v5, 3, v38
	v_mad_u32_u24 v12, v4, s4, v3
	v_ashrrev_i32_e32 v4, 5, v38
	v_and_b32_e32 v11, 24, v5
	v_ashrrev_i32_e32 v5, 31, v4
	v_lshlrev_b64 v[52:53], 13, v[4:5]
	v_mul_lo_u32 v17, v4, s3
	v_add_u32_e32 v4, 0x200, v38
	v_ashrrev_i32_e32 v49, 3, v4
	v_ashrrev_i32_e32 v4, 5, v4
	v_ashrrev_i32_e32 v5, 31, v4
	v_lshlrev_b64 v[54:55], 13, v[4:5]
	v_mul_lo_u32 v19, v4, s3
	v_add_u32_e32 v4, 0x400, v38
	v_bfe_u32 v6, v38, 4, 2
	v_ashrrev_i32_e32 v61, 3, v4
	v_ashrrev_i32_e32 v4, 5, v4
	v_and_b32_e32 v1, 15, v38
	v_lshlrev_b32_e32 v48, 2, v6
	v_ashrrev_i32_e32 v5, 31, v4
	v_and_b32_e32 v42, 64, v38
	v_lshlrev_b32_e32 v46, 1, v1
	v_lshlrev_b64 v[56:57], 13, v[4:5]
	v_mul_lo_u32 v21, v4, s3
	v_add_u32_e32 v4, 0x600, v38
	v_or_b32_e32 v24, 2, v48
	v_and_b32_e32 v13, 48, v38
	v_add_u32_e32 v15, v3, v46
	v_mad_u32_u24 v3, v1, s4, v3
	v_ashrrev_i32_e32 v45, 3, v38
	s_movk_i32 s4, 0x90
	v_ashrrev_i32_e32 v63, 3, v4
	v_ashrrev_i32_e32 v4, 5, v4
	v_or_b32_e32 v60, 16, v42
	v_or_b32_e32 v62, 32, v42
	v_or_b32_e32 v64, 48, v42
	v_or_b32_e32 v23, 1, v48
	v_cmp_ge_u32_e64 s[14:15], v1, v24
	v_cmp_gt_u32_e64 s[16:17], v1, v24
	v_or_b32_e32 v24, 3, v48
	v_and_b32_e32 v44, 0x4f, v38
	v_and_b32_e32 v2, 7, v38
	v_add_u32_e32 v14, 0, v13
	v_mul_lo_u32 v16, v45, s4
	v_mul_lo_u32 v18, v49, s4
	v_mul_lo_u32 v20, v61, s4
	v_mul_lo_u32 v22, v63, s4
	v_ashrrev_i32_e32 v5, 31, v4
	v_cmp_ge_u32_e64 s[4:5], v1, v48
	v_cmp_gt_u32_e64 s[6:7], v1, v48
	v_cmp_gt_u32_e64 s[12:13], v1, v23
	v_cmp_ge_u32_e64 s[18:19], v1, v24
	v_cmp_gt_u32_e64 s[20:21], v1, v24
	v_mul_u32_u24_e32 v25, 0x230, v1
	v_or_b32_e32 v26, v60, v1
	v_or_b32_e32 v28, v62, v1
	v_or_b32_e32 v1, v64, v1
	v_mov_b32_e32 v47, 0
	v_lshlrev_b32_e32 v0, 3, v6
	v_lshl_add_u32 v7, v2, 4, 0
	v_lshlrev_b32_e32 v2, 3, v2
	s_movk_i32 s0, 0xc0
	v_lshlrev_b64 v[58:59], 13, v[4:5]
	v_mul_lo_u32 v4, v4, s3
	v_mul_u32_u24_e32 v5, 0x90, v44
	v_mul_u32_u24_e32 v6, 0x540, v6
	v_mul_u32_u24_e32 v23, 0x150, v23
	v_lshl_add_u32 v24, v42, 1, v14
	v_mul_u32_u24_e32 v26, 0x90, v26
	v_lshl_add_u32 v27, v60, 1, v14
	v_mul_u32_u24_e32 v28, 0x90, v28
	v_lshl_add_u32 v29, v62, 1, v14
	v_mul_u32_u24_e32 v1, 0x90, v1
	v_lshl_add_u32 v30, v64, 1, v14
	v_and_b32_e32 v40, 63, v38
	v_ashrrev_i32_e32 v39, 7, v38
	v_cmp_gt_i32_e64 s[0:1], s0, v38
	v_lshl_add_u64 v[50:51], s[60:61], 0, v[46:47]
	v_cmp_ne_u32_e64 s[8:9], 0, v42
	v_lshlrev_b32_e32 v46, 1, v0
	s_mov_b32 s3, 0x8000
	s_mov_b32 s38, 0x10000
	s_mov_b32 s39, 0x18000
	v_lshlrev_b32_e32 v66, 1, v2
	v_add_u32_e32 v65, v7, v16
	v_add_u32_e32 v76, v8, v17
	v_add_u32_e32 v77, v7, v18
	v_add_u32_e32 v78, v8, v19
	v_add_u32_e32 v79, v7, v20
	v_add_u32_e32 v80, v8, v21
	v_add_u32_e32 v81, v7, v22
	v_add_u32_e32 v82, v8, v4
	v_add_u32_e32 v83, v9, v10
	v_add_u32_e32 v84, v12, v11
	v_add_u32_e32 v85, v14, v5
	s_mov_b32 s42, 0x3e000000
	s_movk_i32 s43, 0x7fff
	v_add_u32_e32 v86, v15, v6
	v_add_u32_e32 v87, v15, v23
	v_add_u32_e32 v88, v3, v13
	v_add_u32_e32 v89, v24, v25
	s_movk_i32 s44, 0x880
	v_add_u32_e32 v90, v14, v26
	v_add_u32_e32 v91, v27, v25
	v_add_u32_e32 v92, v14, v28
	v_add_u32_e32 v93, v29, v25
	v_add_u32_e32 v94, v14, v1
	v_add_u32_e32 v95, v30, v25
	v_mov_b32_e32 v98, v47
	v_mov_b32_e32 v99, v47
	v_mov_b32_e32 v100, v47
	v_mov_b32_e32 v101, v47
	v_mov_b32_e32 v102, v47
	v_mov_b32_e32 v103, v47
	v_mov_b32_e32 v96, 0xff800000
	s_mov_b32 s45, s2
	s_branch .LBB0_2653

.LBB0_2750:
	s_or_b64 exec, exec, s[0:1]
	s_and_b64 vcc, exec, s[72:73]
	s_waitcnt lgkmcnt(0)
	s_barrier
	s_cselect_b32 s99, 1, 0
	s_setprio 0
	s_cmp_lg_u32 s99, 0
	s_cbranch_vccnz .LBB0_2893
	s_add_u32 s4, s84, 0x52a2880
	s_addc_u32 s5, s85, 0
	s_movk_i32 s3, 0x4000
	s_movk_i32 s14, 0x880
	v_mov_b32_e32 v1, 0
	s_mov_b32 s7, 0
	s_movk_i32 s15, 0x6000
	s_add_i32 s16, 0, 0x10000
	s_add_i32 s17, 0, 0x14000
	s_movk_i32 s18, 0x4080
	s_mov_b32 s19, s2
	s_branch .LBB0_2753

.LBB0_2945:
	s_or_b64 exec, exec, s[0:1]
	v_mov_b32_e32 v32, v174
	s_waitcnt lgkmcnt(0)
	s_barrier
	s_cselect_b32 s99, 1, 0
	s_setprio 0
	s_cmp_lg_u32 s99, 0
	s_movk_i32 s3, 0x4080
	v_ashrrev_i32_e32 v0, 6, v32
	v_add_u32_e32 v54, s94, v0
	v_cmp_gt_i32_e32 vcc, s3, v54
	s_and_saveexec_b64 s[4:5], vcc
	s_cbranch_execz .LBB0_2950
	v_lshlrev_b32_e32 v0, 2, v32
	v_and_b32_e32 v34, 0xfc, v0
	v_readlane_b32 s8, v192, 11
	v_mov_b32_e32 v49, 0
	v_lshlrev_b32_e32 v48, 2, v34
	v_readlane_b32 s10, v192, 13
	v_readlane_b32 s11, v192, 14
	s_mov_b64 s[0:1], 0x1000
	v_ashrrev_i32_e32 v55, 31, v54
	v_lshl_add_u64 v[0:1], s[10:11], 0, v[48:49]
	s_waitcnt vmcnt(2)
	v_lshl_add_u64 v[16:17], v[0:1], 0, s[0:1]
	v_add_co_u32_e32 v18, vcc, 0x1000, v0
	v_mbcnt_hi_u32_b32 v33, -1, v175
	s_nop 0
	v_addc_co_u32_e32 v19, vcc, 0, v1, vcc
	global_load_dwordx4 v[0:3], v[16:17], off offset:1024
	global_load_dwordx4 v[4:7], v[16:17], off offset:2048
	global_load_dwordx4 v[8:11], v[18:19], off
	global_load_dwordx4 v[12:15], v[16:17], off offset:3072
	v_lshlrev_b64 v[16:17], 12, v[54:55]
	v_lshl_add_u64 v[16:17], s[82:83], 0, v[16:17]
	v_lshl_add_u64 v[36:37], v[16:17], 0, v[48:49]
	global_load_dwordx4 v[28:31], v[36:37], off
	global_load_dwordx4 v[24:27], v[36:37], off offset:1024
	global_load_dwordx4 v[20:23], v[36:37], off offset:2048
	global_load_dwordx4 v[16:19], v[36:37], off offset:3072
	v_and_b32_e32 v35, 64, v33
	v_add_u32_e32 v35, 64, v35
	v_xor_b32_e32 v36, 32, v33
	v_cmp_lt_i32_e32 vcc, v36, v35
	s_movk_i32 s0, 0x880
	v_readlane_b32 s9, v192, 12
	v_cndmask_b32_e32 v36, v33, v36, vcc
	v_lshlrev_b32_e32 v55, 2, v36
	v_xor_b32_e32 v36, 16, v33
	v_cmp_lt_i32_e32 vcc, v36, v35
	v_readlane_b32 s12, v192, 15
	v_readlane_b32 s13, v192, 16
	v_cndmask_b32_e32 v36, v33, v36, vcc
	v_lshlrev_b32_e32 v56, 2, v36
	v_xor_b32_e32 v36, 8, v33
	v_cmp_lt_i32_e32 vcc, v36, v35
	v_readlane_b32 s16, v192, 19
	v_readlane_b32 s17, v192, 20
	v_cndmask_b32_e32 v36, v33, v36, vcc
	v_lshlrev_b32_e32 v57, 2, v36
	v_xor_b32_e32 v36, 4, v33
	v_cmp_lt_i32_e32 vcc, v36, v35
	v_readlane_b32 s18, v192, 21
	v_readlane_b32 s19, v192, 22
	v_cndmask_b32_e32 v36, v33, v36, vcc
	v_lshlrev_b32_e32 v58, 2, v36
	v_xor_b32_e32 v36, 2, v33
	v_cmp_lt_i32_e32 vcc, v36, v35
	s_ashr_i32 s75, s74, 31
	s_lshl_b64 s[6:7], s[74:75], 12
	v_cndmask_b32_e32 v36, v33, v36, vcc
	v_lshlrev_b32_e32 v59, 2, v36
	v_xor_b32_e32 v36, 1, v33
	v_cmp_lt_i32_e32 vcc, v36, v35
	v_and_b32_e32 v35, 63, v32
	v_lshlrev_b32_e32 v48, 3, v35
	v_cndmask_b32_e32 v33, v33, v36, vcc
	v_lshlrev_b32_e32 v60, 2, v33
	v_mad_i64_i32 v[32:33], s[0:1], v54, s0, v[48:49]
	v_lshl_add_u64 v[32:33], s[84:85], 0, v[32:33]
	s_mov_b64 s[0:1], 0x3018000
	v_lshl_add_u64 v[50:51], v[32:33], 0, s[0:1]
	v_add_u32_e32 v32, s74, v54
	v_ashrrev_i32_e32 v33, 31, v32
	v_lshlrev_b64 v[32:33], 12, v[32:33]
	v_lshl_or_b32 v32, v35, 4, v32
	v_lshl_add_u64 v[52:53], s[82:83], 0, v[32:33]
	s_mov_b64 s[8:9], 0
	s_movk_i32 s16, 0x407f
	s_movk_i32 s17, 0x4000
	s_movk_i32 s18, 0x6000
	v_lshlrev_b32_e32 v48, 2, v34
	s_mov_b64 s[10:11], 0x3000
	s_mov_b64 s[12:13], 0x4000
	v_mov_b32_e32 v61, 0x358637bd
	s_mov_b32 s19, 0x800000
	v_readlane_b32 s14, v192, 17
	v_readlane_b32 s15, v192, 18
	v_readlane_b32 s20, v192, 23
	v_readlane_b32 s21, v192, 24
	v_readlane_b32 s22, v192, 25
	v_readlane_b32 s23, v192, 26
	s_branch .LBB0_2948

.LBB0_3002:
	s_or_b64 exec, exec, s[0:1]
	v_readlane_b32 s52, v192, 55
	s_andn2_b64 vcc, exec, s[56:57]
	v_readlane_b32 s53, v192, 56
	s_waitcnt lgkmcnt(0)
	s_barrier
	s_cselect_b32 s99, 1, 0
	s_setprio 0
	s_cmp_lg_u32 s99, 0
	s_cbranch_vccnz .LBB0_3031
	v_readlane_b32 s0, v192, 35
	v_readlane_b32 s1, v192, 36
	s_movk_i32 s3, 0x880
	v_mov_b64_e32 v[158:159], s[88:89]
	v_mov_b64_e32 v[160:161], s[0:1]
	v_mov_b32_e32 v1, 0
	s_mov_b32 s5, 0
	s_mov_b64 s[6:7], 0x80
	s_add_i32 s8, 0, 0x10000
	s_add_i32 s9, 0, 0x14000
	s_movk_i32 s10, 0x4080
	s_movk_i32 s11, 0x2080
	s_mov_b32 s12, s2
	s_waitcnt vmcnt(0)
	s_branch .LBB0_3005

.LBB0_3083:
	s_or_b64 exec, exec, s[0:1]
	s_and_b64 vcc, exec, s[72:73]
	s_waitcnt lgkmcnt(0)
	s_barrier
	s_cselect_b32 s99, 1, 0
	s_setprio 0
	s_cmp_lg_u32 s99, 0
	s_cbranch_vccnz .LBB0_3226
	s_add_u32 s4, s84, 0x52a5880
	s_addc_u32 s5, s85, 0
	s_movk_i32 s3, 0x4000
	s_movk_i32 s16, 0x2080
	v_mov_b32_e32 v1, 0
	s_mov_b32 s7, 0
	s_movk_i32 s17, 0x6000
	s_mov_b64 s[8:9], 0x80
	s_add_i32 s18, 0, 0x10000
	s_add_i32 s19, 0, 0x14000
	s_movk_i32 s20, 0x4080
	s_branch .LBB0_3086

.LBB0_3278:
	s_or_b64 exec, exec, s[0:1]
	s_waitcnt lgkmcnt(0)
	s_barrier
	s_cselect_b32 s99, 1, 0
	s_setprio 0
	s_cmp_lg_u32 s99, 0
	s_movk_i32 s0, 0x4080
	v_ashrrev_i32_e32 v0, 6, v174
	v_add_u32_e32 v0, s94, v0
	v_cmp_gt_i32_e32 vcc, s0, v0
	s_and_saveexec_b64 s[0:1], vcc
	s_cbranch_execz .LBB0_3281
	v_mbcnt_hi_u32_b32 v1, -1, v175
	v_and_b32_e32 v2, 64, v1
	v_add_u32_e32 v2, 64, v2
	v_xor_b32_e32 v3, 32, v1
	v_cmp_lt_i32_e32 vcc, v3, v2
	v_readlane_b32 s0, v192, 11
	v_readlane_b32 s1, v192, 12
	v_cndmask_b32_e32 v3, v1, v3, vcc
	s_waitcnt vmcnt(0)
	v_lshlrev_b32_e32 v6, 2, v3
	v_xor_b32_e32 v3, 16, v1
	v_cmp_lt_i32_e32 vcc, v3, v2
	v_readlane_b32 s2, v192, 13
	v_readlane_b32 s3, v192, 14
	v_cndmask_b32_e32 v3, v1, v3, vcc
	v_lshlrev_b32_e32 v7, 2, v3
	v_xor_b32_e32 v3, 8, v1
	v_cmp_lt_i32_e32 vcc, v3, v2
	v_readlane_b32 s4, v192, 15
	v_readlane_b32 s5, v192, 16
	v_cndmask_b32_e32 v3, v1, v3, vcc
	v_lshlrev_b32_e32 v8, 2, v3
	v_xor_b32_e32 v3, 4, v1
	v_cmp_lt_i32_e32 vcc, v3, v2
	v_readlane_b32 s12, v192, 23
	v_readlane_b32 s13, v192, 24
	v_cndmask_b32_e32 v3, v1, v3, vcc
	v_lshlrev_b32_e32 v9, 2, v3
	v_xor_b32_e32 v3, 2, v1
	v_cmp_lt_i32_e32 vcc, v3, v2
	s_mov_b64 s[0:1], 0x800
	s_ashr_i32 s75, s74, 31
	v_cndmask_b32_e32 v3, v1, v3, vcc
	v_lshlrev_b32_e32 v10, 2, v3
	v_xor_b32_e32 v3, 1, v1
	v_cmp_lt_i32_e32 vcc, v3, v2
	s_mov_b64 s[2:3], 0
	s_mov_b32 s4, 0x800000
	v_cndmask_b32_e32 v1, v1, v3, vcc
	v_lshlrev_b32_e32 v11, 2, v1
	v_lshlrev_b32_e32 v1, 4, v174
	v_and_b32_e32 v2, 0x3f0, v1
	v_ashrrev_i32_e32 v1, 31, v0
	v_lshlrev_b64 v[4:5], 12, v[0:1]
	v_and_b32_e32 v1, 63, v174
	v_lshl_or_b32 v4, v1, 4, v4
	v_mov_b32_e32 v3, 0
	v_lshl_add_u64 v[4:5], s[82:83], 0, v[4:5]
	v_lshl_add_u64 v[2:3], s[12:13], 0, v[2:3]
	v_lshl_add_u64 v[4:5], v[4:5], 0, s[0:1]
	s_lshl_b64 s[0:1], s[74:75], 12
	v_mov_b32_e32 v1, 0x358637bd
	s_movk_i32 s5, 0x407f
	v_readlane_b32 s6, v192, 17
	v_readlane_b32 s7, v192, 18
	v_readlane_b32 s8, v192, 19
	v_readlane_b32 s9, v192, 20
	v_readlane_b32 s10, v192, 21
	v_readlane_b32 s11, v192, 22
	v_readlane_b32 s14, v192, 25
	v_readlane_b32 s15, v192, 26
